# v088 + nt on P5 x-row loads and P2 raw operand loads
# speedup vs baseline: 1.0261x; 1.0032x over previous
.LBB0_239:
.LBB0_240:
	s_cmp_lt_i32 s72, 3
	s_cselect_b64 s[4:5], -1, 0
	s_add_u32 s48, s70, 0x18c00000
	s_addc_u32 s49, s71, 0
	s_and_b64 s[22:23], s[4:5], s[0:1]
	s_andn2_b64 vcc, exec, s[22:23]
	s_cbranch_vccnz .LBB0_250
	s_cmp_lt_u32 s2, 64
	v_readfirstlane_b32 s3, v143
	s_cbranch_scc1 .LBB0_250
	v_writelane_b32 v240, s2, 0
	v_writelane_b32 v240, s74, 1
	s_mov_b32 s101, s3
	s_sub_u32 s98, s2, 64
	s_and_b32 s99, s98, 63
	s_lshl_b32 s99, s99, 5
	s_lshr_b32 s98, s98, 6
	s_or_b32 s2, s99, s98
	s_add_u32 s100, s99, 32
	s_mov_b32 s74, 3
	s_ashr_i32 s0, s2, 9
	s_ashr_i32 s1, s0, 31
	s_lshl_b32 s4, s2, 6
	v_lshrrev_b32_e32 v56, 7, v143
	s_lshl_b64 s[0:1], s[0:1], 11
	s_and_b32 s4, s4, 0x7c0
	s_or_b32 s0, s0, s4
	s_lshl_b32 s4, s2, 2
	s_waitcnt vmcnt(0)
	v_lshlrev_b32_e32 v22, 4, v56
	v_mov_b32_e32 v23, 0
	v_and_b32_e32 v64, 0x7f, v143
	s_and_b32 s4, s4, 0x780
	v_lshl_add_u64 v[2:3], s[0:1], 0, v[22:23]
	v_or_b32_e32 v58, s4, v64
	v_lshlrev_b64 v[2:3], 11, v[2:3]
	v_readlane_b32 s4, v242, 51
	v_or_b32_e32 v2, v2, v58
	v_readlane_b32 s5, v242, 52
	v_or_b32_e32 v24, 1, v22
	v_mov_b32_e32 v25, v23
	v_lshl_add_u64 v[4:5], v[2:3], 2, s[4:5]
	v_lshlrev_b64 v[2:3], 1, v[2:3]
	v_lshl_add_u64 v[6:7], s[38:39], 0, v[2:3]
	v_lshl_add_u64 v[8:9], s[48:49], 0, v[2:3]
	v_lshl_add_u64 v[2:3], s[0:1], 0, v[24:25]
	v_lshlrev_b64 v[2:3], 11, v[2:3]
	v_or_b32_e32 v2, v2, v58
	v_lshl_add_u64 v[10:11], v[2:3], 2, s[4:5]
	v_lshlrev_b64 v[2:3], 1, v[2:3]
	v_or_b32_e32 v26, 2, v22
	v_mov_b32_e32 v27, v23
	v_lshl_add_u64 v[12:13], s[38:39], 0, v[2:3]
	v_lshl_add_u64 v[14:15], s[48:49], 0, v[2:3]
	v_lshl_add_u64 v[2:3], s[0:1], 0, v[26:27]
	v_lshlrev_b64 v[2:3], 11, v[2:3]
	v_or_b32_e32 v2, v2, v58
	v_lshlrev_b64 v[18:19], 1, v[2:3]
	v_or_b32_e32 v28, 3, v22
	v_mov_b32_e32 v29, v23
	v_or_b32_e32 v30, 4, v22
	v_mov_b32_e32 v31, v23
	v_lshl_add_u64 v[16:17], v[2:3], 2, s[4:5]
	v_lshl_add_u64 v[20:21], s[38:39], 0, v[18:19]
	global_load_dword v2, v[4:5], off nt
	global_load_ushort v65, v[6:7], off nt
	global_load_ushort v66, v[8:9], off nt
	global_load_dword v1, v[10:11], off nt
	global_load_ushort v67, v[12:13], off nt
	global_load_ushort v68, v[14:15], off nt
	global_load_dword v4, v[16:17], off nt
	global_load_ushort v69, v[20:21], off nt
	v_lshl_add_u64 v[8:9], s[0:1], 0, v[28:29]
	v_lshl_add_u64 v[12:13], s[0:1], 0, v[30:31]
	v_lshlrev_b64 v[8:9], 11, v[8:9]
	v_lshlrev_b64 v[14:15], 11, v[12:13]
	v_or_b32_e32 v8, v8, v58
	v_or_b32_e32 v14, v14, v58
	v_lshl_add_u64 v[6:7], s[48:49], 0, v[18:19]
	v_lshl_add_u64 v[16:17], v[8:9], 2, s[4:5]
	v_lshlrev_b64 v[8:9], 1, v[8:9]
	v_lshl_add_u64 v[12:13], v[14:15], 2, s[4:5]
	v_lshlrev_b64 v[14:15], 1, v[14:15]
	v_or_b32_e32 v32, 5, v22
	v_mov_b32_e32 v33, v23
	v_or_b32_e32 v36, 7, v22
	v_mov_b32_e32 v37, v23
	v_lshl_add_u64 v[10:11], s[38:39], 0, v[8:9]
	v_lshl_add_u64 v[8:9], s[48:49], 0, v[8:9]
	v_lshl_add_u64 v[18:19], s[38:39], 0, v[14:15]
	v_lshl_add_u64 v[14:15], s[48:49], 0, v[14:15]
	global_load_ushort v77, v[6:7], off nt
	global_load_ushort v79, v[10:11], off nt
	global_load_ushort v81, v[8:9], off nt
	global_load_ushort v82, v[18:19], off nt
	global_load_ushort v84, v[14:15], off nt
	v_lshl_add_u64 v[6:7], s[0:1], 0, v[32:33]
	v_or_b32_e32 v34, 6, v22
	v_mov_b32_e32 v35, v23
	v_lshl_add_u64 v[38:39], s[0:1], 0, v[36:37]
	v_lshlrev_b64 v[6:7], 11, v[6:7]
	v_lshl_add_u64 v[10:11], s[0:1], 0, v[34:35]
	v_lshlrev_b64 v[38:39], 11, v[38:39]
	v_or_b32_e32 v6, v6, v58
	v_lshlrev_b64 v[10:11], 11, v[10:11]
	v_or_b32_e32 v38, v38, v58
	v_lshl_add_u64 v[18:19], v[6:7], 2, s[4:5]
	v_lshlrev_b64 v[6:7], 1, v[6:7]
	v_or_b32_e32 v10, v10, v58
	v_lshl_add_u64 v[40:41], v[38:39], 2, s[4:5]
	v_lshlrev_b64 v[38:39], 1, v[38:39]
	v_lshl_add_u64 v[8:9], s[38:39], 0, v[6:7]
	v_lshl_add_u64 v[6:7], s[48:49], 0, v[6:7]
	v_lshl_add_u64 v[14:15], v[10:11], 2, s[4:5]
	v_lshlrev_b64 v[10:11], 1, v[10:11]
	v_lshl_add_u64 v[42:43], s[38:39], 0, v[38:39]
	v_lshl_add_u64 v[38:39], s[48:49], 0, v[38:39]
	v_lshl_add_u64 v[20:21], s[38:39], 0, v[10:11]
	v_lshl_add_u64 v[10:11], s[48:49], 0, v[10:11]
	global_load_ushort v70, v[8:9], off nt
	global_load_ushort v71, v[6:7], off nt
	s_nop 0
	global_load_dword v6, v[14:15], off nt
	global_load_ushort v72, v[20:21], off nt
	global_load_ushort v73, v[10:11], off nt
	global_load_dword v7, v[40:41], off nt
	global_load_ushort v74, v[42:43], off nt
	global_load_ushort v75, v[38:39], off nt
	v_or_b32_e32 v38, 8, v22
	v_mov_b32_e32 v39, v23
	v_lshl_add_u64 v[8:9], s[0:1], 0, v[38:39]
	v_lshlrev_b64 v[8:9], 11, v[8:9]
	v_or_b32_e32 v8, v8, v58
	v_lshl_add_u64 v[10:11], v[8:9], 2, s[4:5]
	v_lshlrev_b64 v[8:9], 1, v[8:9]
	v_or_b32_e32 v40, 9, v22
	v_mov_b32_e32 v41, v23
	v_lshl_add_u64 v[14:15], s[38:39], 0, v[8:9]
	v_lshl_add_u64 v[20:21], s[48:49], 0, v[8:9]
	v_lshl_add_u64 v[8:9], s[0:1], 0, v[40:41]
	v_lshlrev_b64 v[8:9], 11, v[8:9]
	v_or_b32_e32 v8, v8, v58
	v_lshl_add_u64 v[44:45], v[8:9], 2, s[4:5]
	v_lshlrev_b64 v[8:9], 1, v[8:9]
	v_or_b32_e32 v42, 10, v22
	v_mov_b32_e32 v43, v23
	v_lshl_add_u64 v[46:47], s[38:39], 0, v[8:9]
	v_lshl_add_u64 v[48:49], s[48:49], 0, v[8:9]
	v_lshl_add_u64 v[8:9], s[0:1], 0, v[42:43]
	v_lshlrev_b64 v[8:9], 11, v[8:9]
	v_or_b32_e32 v8, v8, v58
	v_lshlrev_b64 v[52:53], 1, v[8:9]
	v_lshl_add_u64 v[50:51], v[8:9], 2, s[4:5]
	v_lshl_add_u64 v[54:55], s[38:39], 0, v[52:53]
	global_load_dword v8, v[10:11], off nt
	global_load_ushort v78, v[14:15], off nt
	global_load_ushort v80, v[20:21], off nt
	global_load_dword v9, v[44:45], off nt
	global_load_ushort v83, v[46:47], off nt
	global_load_ushort v85, v[48:49], off nt
	global_load_dword v10, v[50:51], off nt
	global_load_ushort v86, v[54:55], off nt
	v_or_b32_e32 v46, 12, v22
	v_mov_b32_e32 v47, v23
	v_or_b32_e32 v44, 11, v22
	v_mov_b32_e32 v45, v23
	v_lshl_add_u64 v[50:51], s[0:1], 0, v[46:47]
	v_lshl_add_u64 v[20:21], s[0:1], 0, v[44:45]
	v_lshlrev_b64 v[50:51], 11, v[50:51]
	v_lshlrev_b64 v[20:21], 11, v[20:21]
	v_or_b32_e32 v50, v50, v58
	v_or_b32_e32 v20, v20, v58
	v_lshl_add_u64 v[108:109], v[50:51], 2, s[4:5]
	v_lshlrev_b64 v[50:51], 1, v[50:51]
	v_lshl_add_u64 v[14:15], s[48:49], 0, v[52:53]
	v_lshl_add_u64 v[62:63], v[20:21], 2, s[4:5]
	v_lshlrev_b64 v[20:21], 1, v[20:21]
	v_lshl_add_u64 v[52:53], s[38:39], 0, v[50:51]
	v_lshl_add_u64 v[50:51], s[48:49], 0, v[50:51]
	v_lshl_add_u64 v[48:49], s[38:39], 0, v[20:21]
	v_lshl_add_u64 v[20:21], s[48:49], 0, v[20:21]
	global_load_ushort v97, v[14:15], off nt
	global_load_ushort v98, v[48:49], off nt
	global_load_ushort v99, v[20:21], off nt
	global_load_ushort v100, v[52:53], off nt
	global_load_ushort v101, v[50:51], off nt
	v_or_b32_e32 v50, 14, v22
	v_mov_b32_e32 v51, v23
	v_lshl_add_u64 v[52:53], s[0:1], 0, v[50:51]
	v_lshlrev_b64 v[52:53], 11, v[52:53]
	v_or_b32_e32 v52, v52, v58
	v_lshl_add_u64 v[104:105], v[52:53], 2, s[4:5]
	v_lshlrev_b64 v[52:53], 1, v[52:53]
	v_lshl_add_u64 v[106:107], s[38:39], 0, v[52:53]
	v_lshl_add_u64 v[110:111], s[48:49], 0, v[52:53]
	v_or_b32_e32 v52, 15, v22
	v_mov_b32_e32 v53, v23
	v_or_b32_e32 v48, 13, v22
	v_mov_b32_e32 v49, v23
	v_lshl_add_u64 v[54:55], s[0:1], 0, v[52:53]
	v_lshl_add_u64 v[14:15], s[0:1], 0, v[48:49]
	v_lshlrev_b64 v[54:55], 11, v[54:55]
	v_lshlrev_b64 v[14:15], 11, v[14:15]
	v_or_b32_e32 v54, v54, v58
	v_or_b32_e32 v14, v14, v58
	v_lshl_add_u64 v[112:113], v[54:55], 2, s[4:5]
	v_lshlrev_b64 v[54:55], 1, v[54:55]
	v_and_b32_e32 v5, 0x80, v143
	v_lshl_add_u64 v[20:21], v[14:15], 2, s[4:5]
	v_lshl_add_u64 v[114:115], s[38:39], 0, v[54:55]
	v_lshl_add_u64 v[116:117], s[48:49], 0, v[54:55]
	v_cmp_eq_u32_e64 s[0:1], 0, v5
	v_lshl_add_u32 v5, v64, 1, 0
	s_movk_i32 s4, 0x8e
	v_lshlrev_b32_e32 v54, 1, v143
	v_mad_u32_u24 v11, v64, s4, v5
	v_and_b32_e32 v54, 0x600, v54
	s_add_i32 s4, 0, 0x11800
	v_add_u32_e32 v90, s4, v54
	s_lshr_b32 s4, s3, 3
	v_and_b32_e32 v57, 15, v143
	s_and_b32 s6, s4, 0xffffff0
	s_lshr_b32 s7, s3, 2
	s_and_b32 s5, s4, 0xfffffe0
	v_or_b32_e32 v54, s6, v57
	s_movk_i32 s6, 0x110
	s_and_b32 s7, s7, 16
	v_mul_lo_u32 v54, v54, s6
	s_or_b32 s5, s5, s7
	v_add_u32_e32 v92, 0, v54
	v_or_b32_e32 v54, s5, v57
	v_mul_lo_u32 v54, v54, s6
	v_add_u32_e32 v94, 0, v54
	v_lshrrev_b32_e32 v54, 2, v143
	v_and_b32_e32 v54, 12, v54
	v_and_or_b32 v58, s4, 16, v54
	v_lshlrev_b32_e32 v89, 5, v56
	v_or_b32_e32 v57, s7, v57
	v_mul_u32_u24_e32 v87, 0x1100, v56
	v_or_b32_e32 v56, 2, v58
	v_lshlrev_b32_e32 v54, 3, v143
	v_cmp_gt_u32_e64 s[10:11], v56, v57
	v_or_b32_e32 v56, 3, v58
	v_and_b32_e32 v60, 0x1f8, v54
	v_lshlrev_b32_e32 v54, 4, v143
	v_cmp_gt_u32_e64 s[12:13], v56, v57
	v_lshrrev_b32_e32 v56, 4, v143
	s_lshl_b32 s3, s3, 3
	v_and_b32_e32 v55, 0xf0, v54
	v_mul_u32_u24_e32 v118, 0x110, v56
	v_lshrrev_b32_e32 v56, 3, v143
	s_and_b32 s34, s3, 0xfffffe00
	v_add_u32_e32 v95, 0, v55
	v_and_b32_e32 v55, 0x70, v54
	v_mul_u32_u24_e32 v119, 0x90, v56
	v_add_u32_e32 v56, 0x200, v143
	s_ashr_i32 s3, s2, 31
	v_add_u32_e32 v96, 0, v55
	v_mov_b32_e32 v55, v23
	v_cmp_gt_u32_e64 s[6:7], v58, v57
	v_cmp_lt_u32_e64 s[8:9], v58, v57
	v_lshrrev_b32_e32 v57, 4, v56
	v_lshrrev_b32_e32 v56, 3, v56
	s_lshl_b64 s[24:25], s[2:3], 10
	v_mul_u32_u24_e32 v120, 0x110, v57
	v_mul_u32_u24_e32 v121, 0x90, v56
	v_lshl_add_u64 v[56:57], s[24:25], 0, v[54:55]
	s_mov_b64 s[24:25], 0x17200000
	s_ashr_i32 s29, s74, 31
	s_mov_b32 s28, s74
	s_lshl_b64 s[26:27], s[2:3], 14
	v_lshl_add_u64 v[56:57], v[56:57], 0, s[24:25]
	s_lshl_b64 s[24:25], s[28:29], 10
	v_or_b32_e32 v58, s26, v54
	v_mov_b32_e32 v59, s27
	s_lshl_b64 s[26:27], s[28:29], 14
	s_lshl_b64 s[30:31], s[2:3], 12
	v_lshlrev_b64 v[14:15], 1, v[14:15]
	v_lshlrev_b32_e32 v76, 2, v143
	s_add_u32 s3, s34, s30
	v_lshl_add_u64 v[102:103], s[38:39], 0, v[14:15]
	v_lshl_add_u64 v[14:15], s[48:49], 0, v[14:15]
	v_xor_b32_e32 v3, 0x200, v76
	v_mul_u32_u24_e32 v88, 0x110, v24
	s_addc_u32 s30, 0, s31
	s_add_i32 s41, 0, 0x11c00
	v_add_u32_e32 v55, s41, v3
	v_add_u32_e32 v87, v5, v87
	v_add_u32_e32 v88, v5, v88
	v_add_u32_e32 v89, v11, v89
	global_load_ushort v102, v[102:103], off nt
	s_nop 0
	global_load_ushort v103, v[14:15], off nt
	s_nop 0
	global_load_dword v14, v[104:105], off nt
	s_nop 0
	global_load_ushort v104, v[106:107], off nt
	global_load_ushort v105, v[110:111], off nt
	s_nop 0
	global_load_ushort v106, v[114:115], off nt
	global_load_ushort v107, v[116:117], off nt
	global_load_dword v15, v[112:113], off nt
	global_load_dword v5, v[18:19], off nt
	s_nop 0
	global_load_dword v12, v[12:13], off nt
	s_nop 0
	global_load_dword v3, v[16:17], off nt
	global_load_dword v13, v[20:21], off nt
	s_nop 0
	global_load_dword v16, v[108:109], off nt
	global_load_dword v11, v[62:63], off nt
	v_or_b32_e32 v60, s3, v60
	v_mov_b32_e32 v61, s30
	s_mov_b64 s[30:31], 0x16a00000
	v_lshlrev_b32_e32 v91, 2, v64
	v_and_b32_e32 v93, 48, v143
	v_lshl_add_u64 v[60:61], v[60:61], 0, s[30:31]
	s_add_i32 s30, s2, s74
	v_cmp_gt_u32_e64 s[4:5], 64, v143
	s_lshl_b64 s[28:29], s[28:29], 12
	s_lshl_b32 s3, s30, 6
	s_lshl_b32 s36, s74, 6
	s_lshl_b32 s37, s30, 2
	s_lshl_b32 s40, s74, 2
	v_add_u32_e32 v90, v90, v91
	v_add_u32_e32 v91, v92, v93
	v_add_u32_e32 v92, v94, v93
	v_add_u32_e32 v93, v95, v118
	s_brev_b32 s42, 48
	v_add_u32_e32 v94, v96, v119
	s_mov_b32 s43, 0xe000000
	s_brev_b32 s44, 8
	v_add_u32_e32 v95, v95, v120
	v_add_u32_e32 v96, v96, v121
	s_mov_b32 s45, s2
	s_waitcnt vmcnt(0)
	s_branch .LBB0_244

.LBB0_246:
	s_or_b64 exec, exec, s[30:31]
	s_add_i32 s45, s45, s74
	s_waitcnt lgkmcnt(0)
	s_barrier
	s_cmp_ge_i32 s45, s100
	s_cselect_b64 s[30:31], -1, 0
	s_and_b64 vcc, exec, s[30:31]
	s_cbranch_vccnz .LBB0_248
	s_waitcnt vmcnt(0)
	s_ashr_i32 s34, s45, 9
	s_ashr_i32 s35, s34, 31
	s_lshl_b64 s[34:35], s[34:35], 11
	s_and_b32 s46, s3, 0x7c0
	s_or_b32 s34, s34, s46
	s_and_b32 s46, s37, 0x780
	v_lshl_add_u64 v[2:3], s[34:35], 0, v[22:23]
	v_or_b32_e32 v77, s46, v64
	v_lshlrev_b64 v[2:3], 11, v[2:3]
	v_readlane_b32 s46, v242, 51
	v_or_b32_e32 v2, v2, v77
	v_readlane_b32 s47, v242, 52
	v_lshl_add_u64 v[70:71], s[34:35], 0, v[36:37]
	v_lshlrev_b64 v[70:71], 11, v[70:71]
	v_lshl_add_u64 v[4:5], v[2:3], 2, s[46:47]
	v_lshlrev_b64 v[2:3], 1, v[2:3]
	v_lshl_add_u64 v[6:7], s[38:39], 0, v[2:3]
	v_lshl_add_u64 v[8:9], s[48:49], 0, v[2:3]
	v_lshl_add_u64 v[2:3], s[34:35], 0, v[24:25]
	v_lshlrev_b64 v[2:3], 11, v[2:3]
	v_or_b32_e32 v2, v2, v77
	v_lshl_add_u64 v[10:11], v[2:3], 2, s[46:47]
	v_lshlrev_b64 v[2:3], 1, v[2:3]
	v_lshl_add_u64 v[12:13], s[38:39], 0, v[2:3]
	v_lshl_add_u64 v[14:15], s[48:49], 0, v[2:3]
	v_lshl_add_u64 v[2:3], s[34:35], 0, v[26:27]
	v_lshlrev_b64 v[2:3], 11, v[2:3]
	v_or_b32_e32 v2, v2, v77
	v_lshlrev_b64 v[18:19], 1, v[2:3]
	v_lshl_add_u64 v[16:17], v[2:3], 2, s[46:47]
	v_lshl_add_u64 v[20:21], s[38:39], 0, v[18:19]
	global_load_dword v2, v[4:5], off nt
	global_load_ushort v65, v[6:7], off nt
	global_load_ushort v66, v[8:9], off nt
	global_load_dword v1, v[10:11], off nt
	global_load_ushort v67, v[12:13], off nt
	global_load_ushort v68, v[14:15], off nt
	global_load_dword v4, v[16:17], off nt
	global_load_ushort v69, v[20:21], off nt
	v_lshl_add_u64 v[6:7], s[34:35], 0, v[28:29]
	v_lshlrev_b64 v[6:7], 11, v[6:7]
	v_or_b32_e32 v6, v6, v77
	v_lshl_add_u64 v[16:17], v[6:7], 2, s[46:47]
	v_lshlrev_b64 v[6:7], 1, v[6:7]
	v_lshl_add_u64 v[12:13], s[48:49], 0, v[18:19]
	v_lshl_add_u64 v[18:19], s[38:39], 0, v[6:7]
	v_lshl_add_u64 v[20:21], s[48:49], 0, v[6:7]
	v_lshl_add_u64 v[6:7], s[34:35], 0, v[30:31]
	v_lshlrev_b64 v[6:7], 11, v[6:7]
	v_or_b32_e32 v6, v6, v77
	v_lshl_add_u64 v[62:63], v[6:7], 2, s[46:47]
	v_lshlrev_b64 v[6:7], 1, v[6:7]
	v_lshl_add_u64 v[108:109], s[38:39], 0, v[6:7]
	v_lshl_add_u64 v[110:111], s[48:49], 0, v[6:7]
	v_lshl_add_u64 v[6:7], s[34:35], 0, v[32:33]
	v_lshl_add_u64 v[10:11], s[34:35], 0, v[34:35]
	v_lshlrev_b64 v[6:7], 11, v[6:7]
	v_lshlrev_b64 v[10:11], 11, v[10:11]
	v_or_b32_e32 v6, v6, v77
	v_or_b32_e32 v10, v10, v77
	v_lshl_add_u64 v[112:113], v[6:7], 2, s[46:47]
	v_lshlrev_b64 v[6:7], 1, v[6:7]
	v_lshl_add_u64 v[14:15], v[10:11], 2, s[46:47]
	v_lshlrev_b64 v[10:11], 1, v[10:11]
	v_or_b32_e32 v70, v70, v77
	v_lshl_add_u64 v[8:9], s[38:39], 0, v[6:7]
	v_lshl_add_u64 v[6:7], s[48:49], 0, v[6:7]
	v_lshl_add_u64 v[72:73], s[38:39], 0, v[10:11]
	v_lshl_add_u64 v[74:75], v[70:71], 2, s[46:47]
	v_lshlrev_b64 v[70:71], 1, v[70:71]
	v_lshl_add_u64 v[10:11], s[48:49], 0, v[10:11]
	v_lshl_add_u64 v[78:79], s[38:39], 0, v[70:71]
	v_lshl_add_u64 v[80:81], s[48:49], 0, v[70:71]
	global_load_ushort v70, v[8:9], off nt
	global_load_ushort v71, v[6:7], off nt
	s_nop 0
	global_load_dword v6, v[14:15], off nt
	s_nop 0
	global_load_ushort v72, v[72:73], off nt
	s_nop 0
	global_load_ushort v73, v[10:11], off nt
	global_load_dword v7, v[74:75], off nt
	s_nop 0
	global_load_ushort v74, v[78:79], off nt
	global_load_ushort v75, v[80:81], off nt
	v_lshl_add_u64 v[8:9], s[34:35], 0, v[38:39]
	v_lshlrev_b64 v[8:9], 11, v[8:9]
	v_or_b32_e32 v8, v8, v77
	v_lshl_add_u64 v[10:11], v[8:9], 2, s[46:47]
	v_lshlrev_b64 v[8:9], 1, v[8:9]
	v_lshl_add_u64 v[14:15], s[38:39], 0, v[8:9]
	v_lshl_add_u64 v[80:81], s[48:49], 0, v[8:9]
	v_lshl_add_u64 v[8:9], s[34:35], 0, v[40:41]
	v_lshlrev_b64 v[8:9], 11, v[8:9]
	v_or_b32_e32 v8, v8, v77
	v_lshl_add_u64 v[82:83], v[8:9], 2, s[46:47]
	v_lshlrev_b64 v[8:9], 1, v[8:9]
	v_lshl_add_u64 v[84:85], s[38:39], 0, v[8:9]
	v_lshl_add_u64 v[98:99], s[48:49], 0, v[8:9]
	v_lshl_add_u64 v[8:9], s[34:35], 0, v[42:43]
	v_lshlrev_b64 v[8:9], 11, v[8:9]
	v_or_b32_e32 v8, v8, v77
	v_lshlrev_b64 v[102:103], 1, v[8:9]
	v_lshl_add_u64 v[100:101], v[8:9], 2, s[46:47]
	v_lshl_add_u64 v[104:105], s[38:39], 0, v[102:103]
	global_load_dword v8, v[10:11], off nt
	global_load_ushort v78, v[14:15], off nt
	s_nop 0
	global_load_ushort v80, v[80:81], off nt
	s_nop 0
	global_load_dword v9, v[82:83], off nt
	s_nop 0
	global_load_ushort v83, v[84:85], off nt
	s_nop 0
	global_load_ushort v85, v[98:99], off nt
	global_load_dword v10, v[100:101], off nt
	global_load_ushort v86, v[104:105], off nt
	v_lshl_add_u64 v[98:99], s[34:35], 0, v[44:45]
	v_lshlrev_b64 v[98:99], 11, v[98:99]
	v_or_b32_e32 v98, v98, v77
	v_lshl_add_u64 v[114:115], v[98:99], 2, s[46:47]
	v_lshlrev_b64 v[98:99], 1, v[98:99]
	v_lshl_add_u64 v[14:15], s[48:49], 0, v[102:103]
	v_lshl_add_u64 v[100:101], s[38:39], 0, v[98:99]
	v_lshl_add_u64 v[102:103], s[48:49], 0, v[98:99]
	v_lshl_add_u64 v[98:99], s[34:35], 0, v[46:47]
	v_lshlrev_b64 v[98:99], 11, v[98:99]
	v_or_b32_e32 v98, v98, v77
	v_lshl_add_u64 v[116:117], v[98:99], 2, s[46:47]
	v_lshlrev_b64 v[98:99], 1, v[98:99]
	v_lshl_add_u64 v[104:105], s[38:39], 0, v[98:99]
	v_lshl_add_u64 v[106:107], s[48:49], 0, v[98:99]
	global_load_ushort v97, v[14:15], off nt
	global_load_ushort v98, v[100:101], off nt
	global_load_ushort v99, v[102:103], off nt
	s_nop 0
	global_load_ushort v100, v[104:105], off nt
	global_load_ushort v101, v[106:107], off nt
	v_lshl_add_u64 v[104:105], s[34:35], 0, v[50:51]
	v_lshlrev_b64 v[104:105], 11, v[104:105]
	v_or_b32_e32 v104, v104, v77
	v_lshl_add_u64 v[14:15], s[34:35], 0, v[48:49]
	v_lshl_add_u64 v[106:107], v[104:105], 2, s[46:47]
	v_lshlrev_b64 v[104:105], 1, v[104:105]
	v_lshlrev_b64 v[14:15], 11, v[14:15]
	v_lshl_add_u64 v[120:121], s[38:39], 0, v[104:105]
	v_lshl_add_u64 v[122:123], s[48:49], 0, v[104:105]
	v_lshl_add_u64 v[104:105], s[34:35], 0, v[52:53]
	v_or_b32_e32 v14, v14, v77
	v_lshlrev_b64 v[104:105], 11, v[104:105]
	v_lshl_add_u64 v[118:119], v[14:15], 2, s[46:47]
	v_lshlrev_b64 v[14:15], 1, v[14:15]
	v_or_b32_e32 v104, v104, v77
	v_lshl_add_u64 v[102:103], s[38:39], 0, v[14:15]
	v_lshl_add_u64 v[14:15], s[48:49], 0, v[14:15]
	v_lshl_add_u64 v[124:125], v[104:105], 2, s[46:47]
	v_lshlrev_b64 v[104:105], 1, v[104:105]
	v_lshl_add_u64 v[126:127], s[38:39], 0, v[104:105]
	v_lshl_add_u64 v[128:129], s[48:49], 0, v[104:105]
	global_load_ushort v102, v[102:103], off nt
	s_nop 0
	global_load_ushort v103, v[14:15], off nt
	s_nop 0
	global_load_dword v14, v[106:107], off nt
	global_load_ushort v104, v[120:121], off nt
	global_load_ushort v105, v[122:123], off nt
	global_load_dword v15, v[124:125], off nt
	s_nop 0
	global_load_ushort v106, v[126:127], off nt
	global_load_ushort v107, v[128:129], off nt
	global_load_ushort v77, v[12:13], off nt
	global_load_ushort v79, v[18:19], off nt
	global_load_ushort v81, v[20:21], off nt
	global_load_ushort v82, v[108:109], off nt
	global_load_ushort v84, v[110:111], off nt
	global_load_dword v5, v[112:113], off nt
	global_load_dword v12, v[62:63], off nt
	global_load_dword v3, v[16:17], off nt
	global_load_dword v13, v[118:119], off nt
	s_nop 0
	global_load_dword v16, v[116:117], off nt
	global_load_dword v11, v[114:115], off nt

.LBB0_534:
	v_mov_b32_e32 v131, 0
	s_lshl_b64 s[10:11], s[56:57], 12
	v_lshl_add_u64 v[68:69], s[4:5], 0, v[130:131]
	s_movk_i32 s3, 0x1000
	s_add_u32 s10, s40, s10
	v_add_co_u32_e32 v68, vcc, s3, v68
	s_addc_u32 s11, s41, s11
	v_lshlrev_b32_e32 v66, 3, v142
	v_addc_co_u32_e32 v69, vcc, 0, v69, vcc
	global_load_dwordx4 v[114:117], v130, s[4:5] offset:3072 nt
	global_load_dwordx4 v[118:121], v130, s[4:5] offset:2048 nt
	global_load_dwordx4 v[98:101], v[68:69], off offset:3072 nt
	global_load_dwordx4 v[102:105], v[68:69], off offset:2048 nt
	global_load_dwordx4 v[106:109], v[68:69], off offset:1024 nt
	global_load_dwordx4 v[110:113], v[68:69], off nt
	global_load_dwordx4 v[122:125], v130, s[4:5] offset:1024 nt
	global_load_dwordx4 v[126:129], v130, s[4:5] nt
	global_load_dwordx2 v[168:169], v66, s[10:11]
	global_load_dwordx2 v[166:167], v66, s[10:11] offset:512
	global_load_dwordx2 v[164:165], v66, s[10:11] offset:1024
	global_load_dwordx2 v[162:163], v66, s[10:11] offset:1536
	global_load_dwordx2 v[160:161], v66, s[10:11] offset:2048
	global_load_dwordx2 v[158:159], v66, s[10:11] offset:2560
	global_load_dwordx2 v[156:157], v66, s[10:11] offset:3072
	global_load_dwordx2 v[154:155], v66, s[10:11] offset:3584
	v_mbcnt_lo_u32_b32 v68, -1, 0
	v_mbcnt_hi_u32_b32 v68, -1, v68
	v_and_b32_e32 v69, 64, v68
	v_xor_b32_e32 v70, 1, v68
	v_add_u32_e32 v69, 64, v69
	v_xor_b32_e32 v71, 2, v68
	v_cmp_lt_i32_e32 vcc, v70, v69
	v_xor_b32_e32 v72, 4, v68
	v_xor_b32_e32 v73, 8, v68
	v_cndmask_b32_e32 v70, v68, v70, vcc
	v_cmp_lt_i32_e32 vcc, v71, v69
	s_lshl_b64 s[8:9], s[8:9], 12
	v_xor_b32_e32 v74, 16, v68
	v_cndmask_b32_e32 v71, v68, v71, vcc
	v_cmp_lt_i32_e32 vcc, v72, v69
	s_add_u32 s10, s70, s8
	v_mov_b32_e32 v67, v131
	v_cndmask_b32_e32 v72, v68, v72, vcc
	v_cmp_lt_i32_e32 vcc, v73, v69
	v_xor_b32_e32 v75, 32, v68
	s_addc_u32 s11, s71, s9
	v_cndmask_b32_e32 v73, v68, v73, vcc
	v_cmp_lt_i32_e32 vcc, v74, v69
	s_add_i32 s8, s56, s64
	s_mov_b64 s[12:13], 0x1d000000
	v_lshl_add_u64 v[132:133], s[40:41], 0, v[66:67]
	v_cndmask_b32_e32 v74, v68, v74, vcc
	v_cmp_lt_i32_e32 vcc, v75, v69
	s_ashr_i32 s65, s64, 31
	v_lshl_add_u64 v[66:67], s[10:11], 0, v[66:67]
	s_ashr_i32 s9, s8, 31
	v_cndmask_b32_e32 v68, v68, v75, vcc
	s_lshl_b64 s[10:11], s[64:65], 12
	v_lshl_add_u64 v[134:135], v[66:67], 0, s[12:13]
	s_lshl_b64 s[12:13], s[8:9], 13
	v_readlane_b32 s76, v242, 31
	v_lshlrev_b32_e32 v170, 2, v70
	v_lshlrev_b32_e32 v171, 2, v71
	v_lshlrev_b32_e32 v172, 2, v72
	v_lshlrev_b32_e32 v173, 2, v73
	v_lshlrev_b32_e32 v174, 2, v74
	v_lshlrev_b32_e32 v175, 2, v68
	v_readlane_b32 s77, v242, 32
	s_add_u32 s12, s76, s12
	s_mov_b32 s5, 0
	v_mov_b32_e32 v1, 0x358637bd
	s_mov_b32 s3, 0x800000
	s_mov_b32 s26, 0xef000000
	s_mov_b32 s27, 0xef001000
	s_mov_b32 s28, s56
	s_addc_u32 s13, s77, s13
	s_lshl_b64 s[20:21], s[64:65], 13
	s_mov_b64 s[16:17], s[30:31]
	v_readlane_b32 s78, v242, 33
	v_readlane_b32 s79, v242, 34
	v_readlane_b32 s80, v242, 35
	v_readlane_b32 s81, v242, 36
	v_readlane_b32 s82, v242, 37
	v_readlane_b32 s83, v242, 38
	v_readlane_b32 s84, v242, 39
	v_readlane_b32 s85, v242, 40
	v_readlane_b32 s86, v242, 41
	v_readlane_b32 s87, v242, 42
	v_readlane_b32 s88, v242, 43
	s_waitcnt vmcnt(15)
	v_mov_b64_e32 v[66:67], v[114:115]
	s_waitcnt vmcnt(14)
	v_mov_b64_e32 v[70:71], v[118:119]
	s_waitcnt vmcnt(13)
	v_mov_b64_e32 v[82:83], v[98:99]
	s_waitcnt vmcnt(12)
	v_mov_b64_e32 v[86:87], v[102:103]
	s_waitcnt vmcnt(11)
	v_mov_b64_e32 v[90:91], v[106:107]
	s_waitcnt vmcnt(10)
	v_mov_b64_e32 v[94:95], v[110:111]
	s_waitcnt vmcnt(9)
	v_mov_b64_e32 v[74:75], v[122:123]
	s_waitcnt vmcnt(8)
	v_mov_b64_e32 v[78:79], v[126:127]
	v_mov_b64_e32 v[68:69], v[116:117]
	v_mov_b64_e32 v[72:73], v[120:121]
	v_mov_b64_e32 v[84:85], v[100:101]
	v_mov_b64_e32 v[88:89], v[104:105]
	v_mov_b64_e32 v[92:93], v[108:109]
	v_mov_b64_e32 v[96:97], v[112:113]
	v_mov_b64_e32 v[76:77], v[124:125]
	v_mov_b64_e32 v[80:81], v[128:129]
	s_waitcnt vmcnt(7)
	v_mov_b64_e32 v[136:137], v[168:169]
	s_waitcnt vmcnt(6)
	v_mov_b64_e32 v[138:139], v[166:167]
	s_waitcnt vmcnt(5)
	v_mov_b64_e32 v[140:141], v[164:165]
	s_waitcnt vmcnt(4)
	v_mov_b64_e32 v[144:145], v[162:163]
	s_waitcnt vmcnt(3)
	v_mov_b64_e32 v[146:147], v[160:161]
	s_waitcnt vmcnt(2)
	v_mov_b64_e32 v[148:149], v[158:159]
	s_waitcnt vmcnt(1)
	v_mov_b64_e32 v[150:151], v[156:157]
	s_waitcnt vmcnt(0)
	v_mov_b64_e32 v[152:153], v[154:155]
	v_readlane_b32 s89, v242, 44
	v_readlane_b32 s90, v242, 45
	v_readlane_b32 s91, v242, 46
	s_branch .LBB0_537
.LBB0_535:
	v_lshl_add_u64 v[82:83], s[24:25], 0, v[130:131]
	v_add_co_u32_e32 v82, vcc, 0x1000, v82
	s_lshl_b64 s[22:23], s[22:23], 12
	s_nop 0
	v_addc_co_u32_e32 v83, vcc, 0, v83, vcc
	v_lshl_add_u64 v[152:153], v[132:133], 0, s[22:23]
	global_load_dwordx4 v[78:81], v130, s[24:25] nt
	global_load_dwordx4 v[74:77], v130, s[24:25] offset:1024 nt
	global_load_dwordx4 v[70:73], v130, s[24:25] offset:2048 nt
	global_load_dwordx4 v[66:69], v130, s[24:25] offset:3072 nt
	global_load_dwordx4 v[94:97], v[82:83], off nt
	global_load_dwordx4 v[90:93], v[82:83], off offset:1024 nt
	global_load_dwordx4 v[86:89], v[82:83], off offset:2048 nt
	s_nop 0
	global_load_dwordx4 v[82:85], v[82:83], off offset:3072 nt
	s_nop 0
	global_load_dwordx2 v[136:137], v[152:153], off
	global_load_dwordx2 v[138:139], v[152:153], off offset:512
	global_load_dwordx2 v[140:141], v[152:153], off offset:1024
	global_load_dwordx2 v[144:145], v[152:153], off offset:1536
	global_load_dwordx2 v[146:147], v[152:153], off offset:2048
	global_load_dwordx2 v[148:149], v[152:153], off offset:2560
	global_load_dwordx2 v[150:151], v[152:153], off offset:3072
	s_nop 0
	global_load_dwordx2 v[152:153], v[152:153], off offset:3584
